# g1_producers_throttled_5us_per_unit_and_scan_vmcnt0_hoisted
# speedup vs baseline: 1.0220x; 1.0105x over previous
.LBB0_2357:
	s_or_b64 exec, exec, s[0:1]
	s_add_i32 s91, s42, s91
	s_cmpk_lt_i32 s91, 0xc00
	s_cbranch_scc0 .LBB0_2485
	s_sleep 127
	s_sleep 32
